# v36 + out phase: the barrier before the V-tile loads of the retention/GLA tails moved after those loads (they do not depend on the LDS data the barrier guards)
# speedup vs baseline: 1.0036x; 1.0036x over previous
; #define LAS __attribute__((address_space(3)))
; DI int crow(int i, int hh) { return (i & 3) + 8 * (i >> 2) + 4 * hh; }
; #define MFMA32(a, b, c) __builtin_amdgcn_mfma_f32_32x32x16_bf16((a), (b), (c), 0, 0, 0)
; template <int BR> DI void out_item(PARAMS P, int l, int cid, int h, LAS unsigned char* lds, int wave, int lane) {
;     ...
;     __syncthreads();
; #pragma unroll
;     for (int ks = 0; ks < 4; ++ks) {
;         const bf16x8 a = *(const LAS bf16x8*)(Pl + (32 * tt + r) * 72 + 16 * ks + 8 * hh); bf16x8 b;
; #pragma unroll
;         for (int j = 0; j < 8; ++j) b[j] = (short)V[(size_t)(16 * ks + 8 * hh + j) * 512 + 32 * vt + r];
;         o = MFMA32(a, b, o);
;     }
; #pragma unroll
;     for (int i = 0; i < 16; ++i) Ol[(32 * tt + crow(i, hh)) * 132 + 32 * vt + r] = o[i];
;     __syncthreads();
.LBB0_464:
	s_lshl_b64 s[6:7], s[56:57], 10
	s_add_u32 s8, s73, s6
	s_addc_u32 s9, s10, s7
	s_lshl_b32 s3, s3, 8
	s_add_u32 s8, s8, s3
	s_addc_u32 s9, s9, 0
	s_add_u32 s12, s11, s6
	s_addc_u32 s17, s35, s7
	s_add_u32 s16, s12, s3
	s_addc_u32 s17, s17, 0
	v_lshlrev_b32_e32 v32, 1, v60
	v_lshl_add_u64 v[16:17], s[16:17], 0, v[32:33]
	s_movk_i32 s12, 0x1000
	v_add_co_u32_e32 v18, vcc, s12, v16
	s_nop 0
	s_nop 0
	v_addc_co_u32_e32 v19, vcc, 0, v17, vcc
	global_load_ushort v36, v32, s[16:17]
	global_load_ushort v37, v32, s[16:17] offset:1024
	global_load_ushort v35, v32, s[16:17] offset:2048
	s_nop 0
	global_load_ushort v32, v32, s[16:17] offset:3072
	s_nop 0
	global_load_ushort v39, v[18:19], off
	global_load_ushort v40, v[18:19], off offset:1024
	global_load_ushort v41, v[18:19], off offset:2048
	global_load_ushort v42, v[18:19], off offset:3072
	s_movk_i32 s12, 0x4000
	v_add_co_u32_e32 v18, vcc, s12, v16
	s_movk_i32 s12, 0x5000
	s_nop 0
	v_addc_co_u32_e32 v19, vcc, 0, v17, vcc
	v_add_co_u32_e32 v20, vcc, s12, v16
	s_mov_b32 s12, 0x8000
	s_nop 0
	v_addc_co_u32_e32 v21, vcc, 0, v17, vcc
	global_load_ushort v43, v[20:21], off offset:-4096
	global_load_ushort v44, v[18:19], off offset:1024
	global_load_ushort v45, v[18:19], off offset:2048
	global_load_ushort v46, v[18:19], off offset:3072
	global_load_ushort v47, v[20:21], off
	global_load_ushort v48, v[20:21], off offset:1024
	global_load_ushort v49, v[20:21], off offset:2048
	global_load_ushort v71, v[20:21], off offset:3072
	v_add_co_u32_e32 v18, vcc, s12, v16
	s_mov_b32 s12, 0x9000
	s_nop 0
	v_addc_co_u32_e32 v19, vcc, 0, v17, vcc
	v_add_co_u32_e32 v20, vcc, s12, v16
	s_mov_b32 s12, 0xc000
	s_nop 0
	v_addc_co_u32_e32 v21, vcc, 0, v17, vcc
	global_load_ushort v79, v[20:21], off offset:-4096
	global_load_ushort v80, v[18:19], off offset:1024
	global_load_ushort v81, v[18:19], off offset:2048
	global_load_ushort v82, v[18:19], off offset:3072
	global_load_ushort v83, v[20:21], off
	global_load_ushort v84, v[20:21], off offset:1024
	global_load_ushort v85, v[20:21], off offset:2048
	global_load_ushort v86, v[20:21], off offset:3072
	v_add_co_u32_e32 v18, vcc, s12, v16
	s_mov_b32 s12, 0xd000
	s_nop 0
	v_addc_co_u32_e32 v19, vcc, 0, v17, vcc
	v_add_co_u32_e32 v16, vcc, s12, v16
	v_ashrrev_i32_e32 v38, 3, v34
	s_nop 0
	v_addc_co_u32_e32 v17, vcc, 0, v17, vcc
	global_load_ushort v87, v[16:17], off offset:-4096
	global_load_ushort v88, v[18:19], off offset:2048
	global_load_ushort v89, v[16:17], off
	global_load_ushort v90, v[16:17], off offset:2048
	global_load_ushort v91, v[16:17], off offset:3072
	global_load_ushort v92, v[16:17], off offset:1024
	global_load_ushort v93, v[18:19], off offset:3072
	global_load_ushort v94, v[18:19], off offset:1024
	s_waitcnt lgkmcnt(0)
	s_barrier
	ds_read_b128 v[16:19], v76
	ds_read_b128 v[20:23], v76 offset:32
	ds_read_b128 v[24:27], v76 offset:64
	ds_read_b128 v[28:31], v76 offset:96
	v_and_b32_e32 v96, 7, v34
	v_add_u32_e32 v95, v74, v77
	v_add_u32_e32 v97, 0x2400, v95
	v_add_u32_e32 v98, 0x2800, v95
	v_add_u32_e32 v99, 0x3400, v95
	v_add_u32_e32 v100, 0x3800, v95
	s_add_u32 s6, s36, s6
	s_addc_u32 s7, s37, s7
	s_add_u32 s6, s6, s3
	s_addc_u32 s7, s7, 0
	s_waitcnt vmcnt(30)
	v_perm_b32 v34, v37, v36, s26
	s_waitcnt vmcnt(26)
	v_perm_b32 v36, v40, v39, s26
	v_perm_b32 v35, v32, v35, s26
	s_waitcnt vmcnt(24)
	v_perm_b32 v37, v42, v41, s26
	v_ashrrev_i32_e32 v39, 31, v38
	v_lshlrev_b32_e32 v32, 5, v96
	s_waitcnt lgkmcnt(3)
	v_mfma_f32_32x32x16_bf16 v[0:15], v[16:19], v[34:37], v[0:15]
	v_add_u32_e32 v34, 0x4400, v95
	v_add_u32_e32 v35, 0x4800, v95
	s_waitcnt vmcnt(22)
	v_perm_b32 v16, v44, v43, s26
	v_add_u32_e32 v36, 0x5400, v95
	s_waitcnt vmcnt(20)
	v_perm_b32 v17, v46, v45, s26
	v_add_u32_e32 v37, 0x5800, v95
	s_waitcnt vmcnt(18)
	v_perm_b32 v18, v48, v47, s26
	s_waitcnt vmcnt(16)
	v_perm_b32 v19, v71, v49, s26
	s_waitcnt lgkmcnt(2)
	s_nop 0
	v_mfma_f32_32x32x16_bf16 v[0:15], v[20:23], v[16:19], v[0:15]
	v_lshlrev_b64 v[16:17], 10, v[38:39]
	s_waitcnt vmcnt(14)
	v_perm_b32 v18, v80, v79, s26
	s_waitcnt vmcnt(12)
	v_perm_b32 v19, v82, v81, s26
	s_waitcnt vmcnt(10)
	v_perm_b32 v20, v84, v83, s26
	s_waitcnt vmcnt(8)
	v_perm_b32 v21, v86, v85, s26
	s_waitcnt lgkmcnt(1)
	s_nop 0
	v_mfma_f32_32x32x16_bf16 v[0:15], v[24:27], v[18:21], v[0:15]
	v_lshl_add_u64 v[18:19], s[8:9], 0, v[16:17]
	v_lshl_add_u64 v[22:23], v[18:19], 0, v[32:33]
	s_waitcnt vmcnt(3)
	v_perm_b32 v21, v91, v90, s26
	s_waitcnt vmcnt(2)
	v_perm_b32 v20, v92, v89, s26
	s_waitcnt vmcnt(1)
	v_perm_b32 v19, v93, v88, s26
	s_waitcnt vmcnt(0)
	v_perm_b32 v18, v94, v87, s26
	s_waitcnt lgkmcnt(0)
	s_nop 0
	v_mfma_f32_32x32x16_bf16 v[0:15], v[28:31], v[18:21], v[0:15]
	s_nop 11
	ds_write2_b32 v97, v0, v1 offset1:132
	ds_write2_b32 v98, v2, v3 offset0:8 offset1:140
	ds_write2_b32 v99, v4, v5 offset0:32 offset1:164
	ds_write2_b32 v100, v6, v7 offset0:40 offset1:172
	ds_write2_b32 v34, v8, v9 offset0:64 offset1:196
	ds_write2_b32 v35, v10, v11 offset0:72 offset1:204
	ds_write2_b32 v36, v12, v13 offset0:96 offset1:228
	ds_write2_b32 v37, v14, v15 offset0:104 offset1:236
	s_waitcnt lgkmcnt(0)
	s_barrier
; DI float bf2f(bf16_t v) { return __uint_as_float((unsigned)v << 16); }
; template <int BR> DI void out_item(PARAMS P, int l, int cid, int h, LAS unsigned char* lds, int wave, int lane) {
;     ...
;     {
;         const int t = tid >> 3, seg = tid & 7; float ov[16];
; #pragma unroll
;         for (int e = 0; e < 16; ++e) ov[e] = Ol[t * 132 + 16 * seg + e];
;         const bf16_t* gp = GT + (size_t)t * 512 + 16 * seg;
;         f32x4 g0, g1, g2, g3; unpack8(*(const u32x4*)gp, g0, g1); unpack8(*(const u32x4*)(gp + 8), g2, g3);
;         const float gate[16] = {g0[0], g0[1], g0[2], g0[3], g1[0], g1[1], g1[2], g1[3], g2[0], g2[1], g2[2], g2[3], g3[0], g3[1], g3[2], g3[3]};
;         float outv[16];
;         if (BR == 1) {
;             float ps = 0.f;
; #pragma unroll
;             for (int e = 0; e < 8; ++e) ps += bf2f(Pl[t * 72 + 8 * seg + e]);
;             const float* np = (const float*)(P.ws + WS_NP) + (size_t)(cid * 4 + h) * 128 + 16 * seg; const bf16_t* qp = Q + (size_t)t * QW + 16 * seg; float qn = 0.f;
; #pragma unroll
;             for (int e = 0; e < 16; ++e) qn += bf2f(qp[e]) * np[e];
;             ps += __shfl_xor(ps, 1); ps += __shfl_xor(ps, 2); ps += __shfl_xor(ps, 4);
;             qn += __shfl_xor(qn, 1); qn += __shfl_xor(qn, 2); qn += __shfl_xor(qn, 4);
;             const float mg = fmaxf(mp, Gl[t]), den = ps + __expf(mp - mg) * qn, mt = Bl[t] + mg, dd = fmaxf(fabsf(den), __expf(-mt)), inv = 1.f / dd;
; #pragma unroll
;             for (int e = 0; e < 16; ++e) ov[e] *= inv;
;         }
;         float sq = 0.f;
; #pragma unroll
;         for (int e = 0; e < 16; ++e) sq += ov[e] * ov[e];
;         sq += __shfl_xor(sq, 1); sq += __shfl_xor(sq, 2); sq += __shfl_xor(sq, 4);
;         const float rs = rsqrtf(sq * (1.f / 128.f) + EPS);
;         if (BR == 1) {
;             const bf16_t* cp = gb + (size_t)CP_CC * G0ROWS + (size_t)(row0 + t) * 512 + h * 128 + 16 * seg; const float* sk = P.in[18] + l * 512 + h * 128 + 16 * seg;
; #pragma unroll
;             for (int e = 0; e < 16; ++e) outv[e] = gate[e] * (ov[e] * rs + sk[e] * bf2f(cp[e]));
;         } else {
; #pragma unroll
;             for (int e = 0; e < 16; ++e) outv[e] = ov[e] * rs * gate[e];
;         }
;         u32x4 w0, w1;
;         w0.x = cvt_pk_bf16(outv[0], outv[1]); w0.y = cvt_pk_bf16(outv[2], outv[3]); w0.z = cvt_pk_bf16(outv[4], outv[5]); w0.w = cvt_pk_bf16(outv[6], outv[7]);
	global_load_dwordx4 v[0:3], v[22:23], off offset:16
	global_load_dwordx4 v[4:7], v[22:23], off
	v_and_b32_e32 v9, 64, v235
	v_xor_b32_e32 v8, 1, v235
	v_add_u32_e32 v44, 64, v9
	v_mul_lo_u32 v10, v38, s93
	v_lshlrev_b32_e32 v11, 6, v96
	v_cmp_lt_i32_e32 vcc, v8, v44
	v_add3_u32 v22, 0, v10, v11
	s_nop 0
	v_cndmask_b32_e32 v12, v235, v8, vcc
	ds_read_b128 v[8:11], v22 offset:9264
	v_lshlrev_b32_e32 v45, 2, v12
	ds_read_b128 v[12:15], v22 offset:9248
	ds_read_b128 v[18:21], v22 offset:9216
	ds_read_b128 v[22:25], v22 offset:9232
	s_waitcnt lgkmcnt(2)
	v_pk_mul_f32 v[34:35], v[12:13], v[12:13]
	s_waitcnt lgkmcnt(1)
	v_pk_mul_f32 v[42:43], v[18:19], v[18:19]
	v_pk_mul_f32 v[40:41], v[20:21], v[20:21]
	v_add_f32_e32 v42, v42, v43
	v_add_f32_e32 v40, v42, v40
	s_waitcnt lgkmcnt(0)
	v_pk_mul_f32 v[38:39], v[22:23], v[22:23]
	v_add_f32_e32 v40, v40, v41
	v_add_f32_e32 v38, v40, v38
	v_pk_mul_f32 v[36:37], v[24:25], v[24:25]
	v_add_f32_e32 v38, v38, v39
	v_add_f32_e32 v36, v38, v36
	v_add_f32_e32 v36, v36, v37
	v_add_f32_e32 v34, v36, v34
	v_pk_mul_f32 v[30:31], v[14:15], v[14:15]
	v_add_f32_e32 v34, v34, v35
	v_add_f32_e32 v30, v34, v30
	v_pk_mul_f32 v[28:29], v[8:9], v[8:9]
	v_add_f32_e32 v30, v30, v31
	v_add_f32_e32 v28, v30, v28
	v_pk_mul_f32 v[26:27], v[10:11], v[10:11]
	v_add_f32_e32 v28, v28, v29
	v_add_f32_e32 v26, v28, v26
	v_add_f32_e32 v26, v26, v27
	ds_bpermute_b32 v27, v45, v26
	v_xor_b32_e32 v28, 2, v235
	v_cmp_lt_i32_e32 vcc, v28, v44
	s_waitcnt lgkmcnt(0)
	v_add_f32_e32 v26, v26, v27
	v_cndmask_b32_e32 v28, v235, v28, vcc
	v_lshlrev_b32_e32 v28, 2, v28
	ds_bpermute_b32 v27, v28, v26
	v_xor_b32_e32 v28, 4, v235
	v_cmp_lt_i32_e32 vcc, v28, v44
	s_waitcnt lgkmcnt(0)
	v_add_f32_e32 v26, v26, v27
	v_cndmask_b32_e32 v28, v235, v28, vcc
	v_lshlrev_b32_e32 v28, 2, v28
	ds_bpermute_b32 v27, v28, v26
	s_waitcnt lgkmcnt(0)
	v_add_f32_e32 v26, v26, v27
	v_fmamk_f32 v26, v26, 0x3c000000, v229
	v_cmp_gt_f32_e32 vcc, s81, v26
	v_mul_f32_e32 v27, 0x4b800000, v26
	s_waitcnt vmcnt(1)
	v_lshlrev_b32_e32 v28, 16, v3
	v_cndmask_b32_e32 v26, v26, v27, vcc
	v_rsq_f32_e32 v26, v26
	v_and_b32_e32 v29, 0xffff0000, v3
	v_lshlrev_b32_e32 v30, 16, v2
	v_and_b32_e32 v31, 0xffff0000, v2
	v_mul_f32_e32 v27, 0x45800000, v26
	v_cndmask_b32_e32 v26, v26, v27, vcc
	v_pk_mul_f32 v[20:21], v[20:21], v[26:27] op_sel_hi:[1,0]
	v_lshlrev_b32_e32 v2, 16, v1
	v_and_b32_e32 v3, 0xffff0000, v1
	v_lshlrev_b32_e32 v34, 16, v0
	v_and_b32_e32 v35, 0xffff0000, v0
	s_waitcnt vmcnt(0)
	v_lshlrev_b32_e32 v0, 16, v7
	v_and_b32_e32 v1, 0xffff0000, v7
	v_lshlrev_b32_e32 v36, 16, v6
	v_and_b32_e32 v37, 0xffff0000, v6
	v_lshlrev_b32_e32 v6, 16, v5
	v_and_b32_e32 v7, 0xffff0000, v5
	v_pk_mul_f32 v[6:7], v[20:21], v[6:7]
	v_pk_mul_f32 v[20:21], v[24:25], v[26:27] op_sel_hi:[1,0]
	v_pk_mul_f32 v[18:19], v[18:19], v[26:27] op_sel_hi:[1,0]
	v_pk_mul_f32 v[20:21], v[20:21], v[0:1]
	v_pk_mul_f32 v[0:1], v[12:13], v[26:27] op_sel_hi:[1,0]
	v_pk_mul_f32 v[22:23], v[22:23], v[26:27] op_sel_hi:[1,0]
	v_pk_mul_f32 v[12:13], v[0:1], v[34:35]
	v_pk_mul_f32 v[0:1], v[14:15], v[26:27] op_sel_hi:[1,0]
	v_lshlrev_b32_e32 v38, 16, v4
	v_pk_mul_f32 v[14:15], v[0:1], v[2:3]
	v_pk_mul_f32 v[0:1], v[8:9], v[26:27] op_sel_hi:[1,0]
	v_and_b32_e32 v39, 0xffff0000, v4
	v_pk_mul_f32 v[8:9], v[0:1], v[30:31]
	v_pk_mul_f32 v[0:1], v[10:11], v[26:27] op_sel_hi:[1,0]
	v_pk_mul_f32 v[4:5], v[18:19], v[38:39]
	v_pk_mul_f32 v[18:19], v[22:23], v[36:37]
	v_pk_mul_f32 v[10:11], v[0:1], v[28:29]
	v_cvt_pk_bf16_f32 v1, v6, v7
	v_cvt_pk_bf16_f32 v6, v8, v9
	v_lshl_add_u64 v[8:9], s[6:7], 0, v[16:17]
	v_cvt_pk_bf16_f32 v0, v4, v5
	v_cvt_pk_bf16_f32 v2, v18, v19
	v_cvt_pk_bf16_f32 v3, v20, v21
	v_lshl_add_u64 v[8:9], v[8:9], 0, v[32:33]
	v_cvt_pk_bf16_f32 v4, v12, v13
	v_cvt_pk_bf16_f32 v5, v14, v15
	v_cvt_pk_bf16_f32 v7, v10, v11
	global_store_dwordx4 v[8:9], v[0:3], off
	global_store_dwordx4 v[8:9], v[4:7], off offset:16
	s_barrier

; #define LAS __attribute__((address_space(3)))
; DI int crow(int i, int hh) { return (i & 3) + 8 * (i >> 2) + 4 * hh; }
; #define MFMA32(a, b, c) __builtin_amdgcn_mfma_f32_32x32x16_bf16((a), (b), (c), 0, 0, 0)
; template <int BR> DI void out_item(PARAMS P, int l, int cid, int h, LAS unsigned char* lds, int wave, int lane) {
;     ...
;     __syncthreads();
; #pragma unroll
;     for (int ks = 0; ks < 4; ++ks) {
;         const bf16x8 a = *(const LAS bf16x8*)(Pl + (32 * tt + r) * 72 + 16 * ks + 8 * hh); bf16x8 b;
; #pragma unroll
;         for (int j = 0; j < 8; ++j) b[j] = (short)V[(size_t)(16 * ks + 8 * hh + j) * 512 + 32 * vt + r];
;         o = MFMA32(a, b, o);
;     }
; #pragma unroll
;     for (int i = 0; i < 16; ++i) Ol[(32 * tt + crow(i, hh)) * 132 + 32 * vt + r] = o[i];
;     __syncthreads();
.LBB0_515:
	s_lshl_b64 s[6:7], s[56:57], 10
	s_add_u32 s16, s64, s6
	s_addc_u32 s17, s65, s7
	s_lshl_b32 s12, s3, 8
	s_add_u32 s16, s16, s12
	s_addc_u32 s17, s17, 0
	v_lshlrev_b32_e32 v16, 1, v60
	s_nop 0
	global_load_ushort v35, v16, s[16:17] offset:3072
	v_mov_b32_e32 v17, v33
	v_lshl_add_u64 v[18:19], s[16:17], 0, v[16:17]
	s_movk_i32 s20, 0x1000
	v_add_co_u32_e32 v20, vcc, s20, v18
	s_movk_i32 s20, 0x4000
	s_nop 0
	v_addc_co_u32_e32 v21, vcc, 0, v19, vcc
	v_add_co_u32_e32 v22, vcc, s20, v18
	s_movk_i32 s20, 0x5000
	s_nop 0
	v_addc_co_u32_e32 v23, vcc, 0, v19, vcc
	v_add_co_u32_e32 v24, vcc, s20, v18
	s_mov_b32 s20, 0x8000
	s_nop 0
	v_addc_co_u32_e32 v25, vcc, 0, v19, vcc
	v_add_co_u32_e32 v26, vcc, s20, v18
	s_mov_b32 s20, 0x9000
	s_nop 0
	v_addc_co_u32_e32 v27, vcc, 0, v19, vcc
	v_add_co_u32_e32 v28, vcc, s20, v18
	v_add_u32_e32 v96, v74, v77
	s_nop 0
	v_addc_co_u32_e32 v29, vcc, 0, v19, vcc
	global_load_ushort v38, v[20:21], off
	global_load_ushort v41, v[20:21], off offset:1024
	global_load_ushort v39, v[20:21], off offset:2048
	global_load_ushort v42, v[20:21], off offset:3072
	global_load_ushort v43, v[22:23], off offset:1024
	global_load_ushort v44, v[22:23], off offset:2048
	global_load_ushort v45, v[22:23], off offset:3072
	global_load_ushort v46, v[26:27], off offset:1024
	global_load_ushort v36, v16, s[16:17]
	global_load_ushort v47, v16, s[16:17] offset:1024
	global_load_ushort v37, v16, s[16:17] offset:2048
	global_load_ushort v48, v[26:27], off offset:2048
	global_load_ushort v49, v[26:27], off offset:3072
	global_load_ushort v71, v[24:25], off offset:-4096
	global_load_ushort v79, v[24:25], off
	global_load_ushort v80, v[24:25], off offset:1024
	global_load_ushort v81, v[24:25], off offset:2048
	global_load_ushort v82, v[24:25], off offset:3072
	global_load_ushort v83, v[28:29], off offset:-4096
	global_load_ushort v84, v[28:29], off
	global_load_ushort v85, v[28:29], off offset:1024
	global_load_ushort v86, v[28:29], off offset:2048
	global_load_ushort v87, v[28:29], off offset:3072
	s_mov_b32 s16, 0xc000
	v_add_co_u32_e32 v16, vcc, s16, v18
	s_mov_b32 s16, 0xd000
	s_nop 0
	v_addc_co_u32_e32 v17, vcc, 0, v19, vcc
	v_add_co_u32_e32 v18, vcc, s16, v18
	s_add_u32 s16, s97, s6
	s_nop 0
	v_addc_co_u32_e32 v19, vcc, 0, v19, vcc
	global_load_ushort v88, v[18:19], off offset:-4096
	global_load_ushort v89, v[18:19], off
	global_load_ushort v90, v[18:19], off offset:1024
	global_load_ushort v91, v[18:19], off offset:2048
	global_load_ushort v92, v[18:19], off offset:3072
	global_load_ushort v93, v[16:17], off offset:2048
	global_load_ushort v94, v[16:17], off offset:3072
	global_load_ushort v95, v[16:17], off offset:1024
	s_waitcnt lgkmcnt(0)
	s_barrier
	ds_read_b128 v[16:19], v76
	ds_read_b128 v[20:23], v76 offset:32
	ds_read_b128 v[24:27], v76 offset:64
	ds_read_b128 v[28:31], v76 offset:96
	v_ashrrev_i32_e32 v40, 3, v34
	s_addc_u32 s17, s18, s7
	v_add_u32_e32 v97, 0x2400, v96
	s_add_u32 s16, s16, s12
	v_add_u32_e32 v98, 0x2800, v96
	v_add_u32_e32 v99, 0x3400, v96
	s_addc_u32 s17, s17, 0
	s_add_u32 s6, s19, s6
	s_addc_u32 s7, s2, s7
	s_add_u32 s6, s6, s12
	s_addc_u32 s7, s7, 0
	s_waitcnt vmcnt(29)
	v_perm_b32 v38, v41, v38, s26
	v_ashrrev_i32_e32 v41, 31, v40
	s_waitcnt vmcnt(27)
	v_perm_b32 v39, v42, v39, s26
	s_waitcnt vmcnt(21)
	v_perm_b32 v36, v47, v36, s26
	s_waitcnt vmcnt(20)
	v_perm_b32 v37, v35, v37, s26
	v_add_u32_e32 v35, 0x3800, v96
	s_waitcnt lgkmcnt(3)
	v_mfma_f32_32x32x16_bf16 v[0:15], v[16:19], v[36:39], v[0:15]
	v_perm_b32 v17, v45, v44, s26
	s_waitcnt vmcnt(15)
	v_perm_b32 v18, v80, v79, s26
	v_perm_b32 v16, v43, v71, s26
	s_waitcnt vmcnt(13)
	v_perm_b32 v19, v82, v81, s26
	v_add_u32_e32 v36, 0x4400, v96
	v_add_u32_e32 v37, 0x4800, v96
	s_waitcnt lgkmcnt(2)
	v_mfma_f32_32x32x16_bf16 v[0:15], v[20:23], v[16:19], v[0:15]
	s_waitcnt vmcnt(8)
	v_perm_b32 v19, v87, v86, s26
	v_perm_b32 v18, v85, v84, s26
	v_perm_b32 v17, v49, v48, s26
	v_perm_b32 v16, v46, v83, s26
	v_add_u32_e32 v20, 0x5400, v96
	v_add_u32_e32 v21, 0x5800, v96
	s_waitcnt lgkmcnt(1)
	v_mfma_f32_32x32x16_bf16 v[0:15], v[24:27], v[16:19], v[0:15]
	s_waitcnt vmcnt(5)
	v_perm_b32 v18, v90, v89, s26
	s_waitcnt vmcnt(3)
	v_perm_b32 v19, v92, v91, s26
	v_lshlrev_b64 v[24:25], 10, v[40:41]
	s_waitcnt vmcnt(1)
	v_perm_b32 v17, v94, v93, s26
	s_waitcnt vmcnt(0)
	v_perm_b32 v16, v95, v88, s26
	v_mov_b32_e32 v27, v33
	s_waitcnt lgkmcnt(0)
	v_mfma_f32_32x32x16_bf16 v[0:15], v[28:31], v[16:19], v[0:15]
	s_nop 11
	ds_write2_b32 v97, v0, v1 offset1:132
	ds_write2_b32 v98, v2, v3 offset0:8 offset1:140
	ds_write2_b32 v99, v4, v5 offset0:32 offset1:164
	ds_write2_b32 v35, v6, v7 offset0:40 offset1:172
	ds_write2_b32 v36, v8, v9 offset0:64 offset1:196
	ds_write2_b32 v37, v10, v11 offset0:72 offset1:204
	ds_write2_b32 v20, v12, v13 offset0:96 offset1:228
	ds_write2_b32 v21, v14, v15 offset0:104 offset1:236
	v_and_b32_e32 v8, 7, v34
	v_lshl_add_u64 v[0:1], s[16:17], 0, v[24:25]
	v_lshlrev_b32_e32 v26, 5, v8
	v_lshl_add_u64 v[4:5], v[0:1], 0, v[26:27]
	s_waitcnt lgkmcnt(0)
	s_barrier
; DI float bf2f(bf16_t v) { return __uint_as_float((unsigned)v << 16); }
; template <int BR> DI void out_item(PARAMS P, int l, int cid, int h, LAS unsigned char* lds, int wave, int lane) {
;     ...
;     {
;         const int t = tid >> 3, seg = tid & 7; float ov[16];
; #pragma unroll
;         for (int e = 0; e < 16; ++e) ov[e] = Ol[t * 132 + 16 * seg + e];
;         const bf16_t* gp = GT + (size_t)t * 512 + 16 * seg;
;         f32x4 g0, g1, g2, g3; unpack8(*(const u32x4*)gp, g0, g1); unpack8(*(const u32x4*)(gp + 8), g2, g3);
;         const float gate[16] = {g0[0], g0[1], g0[2], g0[3], g1[0], g1[1], g1[2], g1[3], g2[0], g2[1], g2[2], g2[3], g3[0], g3[1], g3[2], g3[3]};
;         float outv[16];
;         if (BR == 1) {
;             float ps = 0.f;
; #pragma unroll
;             for (int e = 0; e < 8; ++e) ps += bf2f(Pl[t * 72 + 8 * seg + e]);
;             const float* np = (const float*)(P.ws + WS_NP) + (size_t)(cid * 4 + h) * 128 + 16 * seg; const bf16_t* qp = Q + (size_t)t * QW + 16 * seg; float qn = 0.f;
; #pragma unroll
;             for (int e = 0; e < 16; ++e) qn += bf2f(qp[e]) * np[e];
;             ps += __shfl_xor(ps, 1); ps += __shfl_xor(ps, 2); ps += __shfl_xor(ps, 4);
;             qn += __shfl_xor(qn, 1); qn += __shfl_xor(qn, 2); qn += __shfl_xor(qn, 4);
;             const float mg = fmaxf(mp, Gl[t]), den = ps + __expf(mp - mg) * qn, mt = Bl[t] + mg, dd = fmaxf(fabsf(den), __expf(-mt)), inv = 1.f / dd;
; #pragma unroll
;             for (int e = 0; e < 16; ++e) ov[e] *= inv;
;         }
;         float sq = 0.f;
; #pragma unroll
;         for (int e = 0; e < 16; ++e) sq += ov[e] * ov[e];
;         sq += __shfl_xor(sq, 1); sq += __shfl_xor(sq, 2); sq += __shfl_xor(sq, 4);
;         const float rs = rsqrtf(sq * (1.f / 128.f) + EPS);
;         if (BR == 1) {
;             const bf16_t* cp = gb + (size_t)CP_CC * G0ROWS + (size_t)(row0 + t) * 512 + h * 128 + 16 * seg; const float* sk = P.in[18] + l * 512 + h * 128 + 16 * seg;
; #pragma unroll
;             for (int e = 0; e < 16; ++e) outv[e] = gate[e] * (ov[e] * rs + sk[e] * bf2f(cp[e]));
;         } else {
; #pragma unroll
;             for (int e = 0; e < 16; ++e) outv[e] = ov[e] * rs * gate[e];
;         }
;         u32x4 w0, w1;
;         w0.x = cvt_pk_bf16(outv[0], outv[1]); w0.y = cvt_pk_bf16(outv[2], outv[3]); w0.z = cvt_pk_bf16(outv[4], outv[5]); w0.w = cvt_pk_bf16(outv[6], outv[7]);
	global_load_dwordx4 v[0:3], v[4:5], off offset:16
	s_nop 0
	global_load_dwordx4 v[4:7], v[4:5], off
	v_and_b32_e32 v9, 64, v235
	v_xor_b32_e32 v16, 1, v235
	v_add_u32_e32 v46, 64, v9
	v_mul_lo_u32 v10, v40, s93
	v_lshlrev_b32_e32 v8, 6, v8
	v_cmp_lt_i32_e32 vcc, v16, v46
	v_add3_u32 v20, 0, v10, v8
	ds_read_b128 v[8:11], v20 offset:9248
	ds_read_b128 v[12:15], v20 offset:9264
	v_cndmask_b32_e32 v16, v235, v16, vcc
	v_lshlrev_b32_e32 v47, 2, v16
	ds_read_b128 v[16:19], v20 offset:9216
	ds_read_b128 v[20:23], v20 offset:9232
	s_waitcnt lgkmcnt(3)
	v_pk_mul_f32 v[36:37], v[8:9], v[8:9]
	v_pk_mul_f32 v[34:35], v[10:11], v[10:11]
	s_waitcnt lgkmcnt(2)
	v_pk_mul_f32 v[30:31], v[12:13], v[12:13]
	s_waitcnt lgkmcnt(1)
	v_pk_mul_f32 v[44:45], v[16:17], v[16:17]
	v_pk_mul_f32 v[42:43], v[18:19], v[18:19]
	v_add_f32_e32 v44, v44, v45
	v_add_f32_e32 v42, v44, v42
	s_waitcnt lgkmcnt(0)
	v_pk_mul_f32 v[40:41], v[20:21], v[20:21]
	v_add_f32_e32 v42, v42, v43
	v_add_f32_e32 v40, v42, v40
	v_pk_mul_f32 v[38:39], v[22:23], v[22:23]
	v_add_f32_e32 v40, v40, v41
	v_add_f32_e32 v38, v40, v38
	v_add_f32_e32 v38, v38, v39
	v_add_f32_e32 v36, v38, v36
	v_add_f32_e32 v36, v36, v37
	v_add_f32_e32 v34, v36, v34
	v_add_f32_e32 v34, v34, v35
	v_add_f32_e32 v30, v34, v30
	v_pk_mul_f32 v[28:29], v[14:15], v[14:15]
	v_add_f32_e32 v30, v30, v31
	v_add_f32_e32 v28, v30, v28
	v_add_f32_e32 v28, v28, v29
	ds_bpermute_b32 v29, v47, v28
	v_xor_b32_e32 v30, 2, v235
	v_cmp_lt_i32_e32 vcc, v30, v46
	s_mov_b64 s[16:17], 0
	s_waitcnt lgkmcnt(0)
	v_add_f32_e32 v28, v28, v29
	v_cndmask_b32_e32 v30, v235, v30, vcc
	v_lshlrev_b32_e32 v30, 2, v30
	ds_bpermute_b32 v29, v30, v28
	v_xor_b32_e32 v30, 4, v235
	v_cmp_lt_i32_e32 vcc, v30, v46
	s_waitcnt lgkmcnt(0)
	v_add_f32_e32 v28, v28, v29
	v_cndmask_b32_e32 v30, v235, v30, vcc
	v_lshlrev_b32_e32 v30, 2, v30
	ds_bpermute_b32 v29, v30, v28
	s_waitcnt lgkmcnt(0)
	v_add_f32_e32 v28, v28, v29
	v_fmamk_f32 v28, v28, 0x3c000000, v229
	v_mul_f32_e32 v29, 0x4b800000, v28
	v_cmp_gt_f32_e32 vcc, s81, v28
	s_waitcnt vmcnt(1)
	v_lshlrev_b32_e32 v30, 16, v2
	v_cndmask_b32_e32 v28, v28, v29, vcc
	v_rsq_f32_e32 v40, v28
	s_waitcnt vmcnt(0)
	v_lshlrev_b32_e32 v38, 16, v4
	v_and_b32_e32 v39, 0xffff0000, v4
	v_lshlrev_b32_e32 v28, 16, v3
	v_mul_f32_e32 v4, 0x45800000, v40
	v_cndmask_b32_e32 v4, v40, v4, vcc
	v_and_b32_e32 v29, 0xffff0000, v3
	v_and_b32_e32 v31, 0xffff0000, v2
	v_lshlrev_b32_e32 v2, 16, v1
	v_and_b32_e32 v3, 0xffff0000, v1
	v_lshlrev_b32_e32 v34, 16, v0
	v_and_b32_e32 v35, 0xffff0000, v0
	v_lshlrev_b32_e32 v0, 16, v7
	v_and_b32_e32 v1, 0xffff0000, v7
	v_lshlrev_b32_e32 v36, 16, v6
	v_and_b32_e32 v37, 0xffff0000, v6
	v_lshlrev_b32_e32 v6, 16, v5
	v_and_b32_e32 v7, 0xffff0000, v5
	v_pk_mul_f32 v[18:19], v[18:19], v[4:5] op_sel_hi:[1,0]
	v_pk_mul_f32 v[16:17], v[16:17], v[4:5] op_sel_hi:[1,0]
	v_pk_mul_f32 v[6:7], v[18:19], v[6:7]
	v_pk_mul_f32 v[18:19], v[20:21], v[4:5] op_sel_hi:[1,0]
	v_pk_mul_f32 v[20:21], v[22:23], v[4:5] op_sel_hi:[1,0]
	v_pk_mul_f32 v[16:17], v[16:17], v[38:39]
	v_pk_mul_f32 v[20:21], v[20:21], v[0:1]
	v_pk_mul_f32 v[0:1], v[8:9], v[4:5] op_sel_hi:[1,0]
	v_pk_mul_f32 v[18:19], v[18:19], v[36:37]
	v_pk_mul_f32 v[8:9], v[0:1], v[34:35]
	v_pk_mul_f32 v[0:1], v[10:11], v[4:5] op_sel_hi:[1,0]
	s_nop 0
	v_pk_mul_f32 v[10:11], v[0:1], v[2:3]
	v_pk_mul_f32 v[0:1], v[12:13], v[4:5] op_sel_hi:[1,0]
	v_cvt_pk_bf16_f32 v2, v18, v19
	v_pk_mul_f32 v[12:13], v[0:1], v[30:31]
	v_pk_mul_f32 v[0:1], v[14:15], v[4:5] op_sel_hi:[1,0]
	v_cvt_pk_bf16_f32 v4, v8, v9
	v_lshl_add_u64 v[8:9], s[6:7], 0, v[24:25]
	v_pk_mul_f32 v[14:15], v[0:1], v[28:29]
	v_cvt_pk_bf16_f32 v0, v16, v17
	v_cvt_pk_bf16_f32 v1, v6, v7
	v_cvt_pk_bf16_f32 v3, v20, v21
	v_lshl_add_u64 v[8:9], v[8:9], 0, v[26:27]
	v_cvt_pk_bf16_f32 v5, v10, v11
	v_cvt_pk_bf16_f32 v6, v12, v13
	v_cvt_pk_bf16_f32 v7, v14, v15
	global_store_dwordx4 v[8:9], v[0:3], off
	global_store_dwordx4 v[8:9], v[4:7], off offset:16
	s_barrier
